# GEMM main loop: the 16 LDS-DMA loads per trip use SGPR base + 32-bit lane offset instead of a 64-bit VALU add each (on top of the attention loop changes)
# speedup vs baseline: 1.0592x; 1.0047x over previous
; #define PG8_STAGE(bufoff, gbase, voff) do { _Pragma("unroll") for (int _i = 0; _i < 2; ++_i) \
;         __builtin_amdgcn_global_load_lds((const unsigned*)((const char*)(gbase) + (voff)[_i]), (LAS unsigned*)(lds + (bufoff) + ldsw + _i * 8192), 16, 0, 0); } while (0)
; #define PG8_LDA(dst, b, h) do { _Pragma("unroll") for (int m = 0; m < 4; ++m) _Pragma("unroll") for (int k = 0; k < 2; ++k) dst[m][k] = *(const LAS bf16x8*)(lds + PG8_SA(b, h) + aoff + m * 2048 + k * 1024); } while (0)
; #define PG8_LDB(dst, b, h) do { _Pragma("unroll") for (int n = 0; n < 2; ++n) _Pragma("unroll") for (int k = 0; k < 2; ++k) dst[n][k] = *(const LAS bf16x8*)(lds + PG8_SB(b, h) + boff + n * 2048 + k * 1024); } while (0)
; #define PG8_MMA(ai, bj, At, Bt) do { __builtin_amdgcn_s_setprio(1); _Pragma("unroll") for (int m = 0; m < 4; ++m) _Pragma("unroll") for (int n = 0; n < 2; ++n) _Pragma("unroll") for (int k = 0; k < 2; ++k) \
;         acc[ai][bj][m][n] = __builtin_amdgcn_mfma_f32_16x16x32_bf16(Bt[n][k], At[m][k], acc[ai][bj][m][n], 0, 0, 0); __builtin_amdgcn_s_setprio(0); } while (0)
; #define PG8_WAIT_V(n) asm volatile("s_waitcnt vmcnt(" #n ")" ::: "memory")
; #define PG8_WAIT_L(n) asm volatile("s_waitcnt lgkmcnt(" #n ")" ::: "memory")
; #define PG8_BAR __builtin_amdgcn_s_barrier()
; #define PG8_SCHED __builtin_amdgcn_sched_barrier(0)
; template <class EpiT>
; __device__ __forceinline__ void gemm_phase(LAS unsigned char* lds, const Gemm g, const StaticOrder& S, const EpiT& E, int wv) {
;     ...
;         for (int t = 0; t < nt; t += 2) {
;             const bool last = (t == nt - 2);
;             const char* a1 = cA + (size_t)(t + 1) * kstep;
;             const char* a2 = last ? nA : cA + (size_t)(t + 2) * kstep; const char* b2 = last ? nB : cB + (size_t)(t + 2) * kstep;
;             const char* a3 = a2 + kstep; const char* b3 = b2 + kstep;
;             PG8_LDB(B0, 0, 0); PG8_LDB(B1, 0, 1); PG8_SCHED; PG8_LDA(At, 0, 0); PG8_STAGE(PG8_SA(1, 1), a1 + hA, voffA);
;             PG8_WAIT_V(8); PG8_WAIT_L(0); PG8_BAR; PG8_MMA(0, 0, At, B0); PG8_MMA(0, 1, At, B1); PG8_BAR; PG8_SCHED;
;             PG8_LDA(At, 0, 1); PG8_STAGE(PG8_SB(0, 0), b2, voffB); PG8_STAGE(PG8_SB(0, 1), b2 + hB, voffB); PG8_STAGE(PG8_SA(0, 0), a2, voffA);
;             PG8_WAIT_V(8); PG8_WAIT_L(0); PG8_BAR; PG8_MMA(1, 0, At, B0); PG8_MMA(1, 1, At, B1); PG8_BAR; PG8_SCHED;
.LBB0_271:
	s_add_i32 s42, s22, 2
	s_add_u32 s43, s0, 0x80
	s_addc_u32 s23, s1, 0
	s_add_i32 s64, 0, 0x10000
	s_cmp_eq_u32 s52, s22
	s_cselect_b32 s23, s19, s23
	s_cselect_b32 s22, s18, s43
	v_add_u32_e32 v0, s64, v234
	s_cselect_b32 s45, s21, s41
	s_cselect_b32 s44, s20, s40
	s_add_i32 s43, 0, 0x14000
	ds_read_b128 v[134:137], v0
	ds_read_b128 v[138:141], v0 offset:1024
	ds_read_b128 v[142:145], v0 offset:2048
	ds_read_b128 v[146:149], v0 offset:3072
	v_add_u32_e32 v0, s43, v234
	ds_read_b128 v[150:153], v0
	ds_read_b128 v[154:157], v0 offset:1024
	ds_read_b128 v[158:161], v0 offset:2048
	ds_read_b128 v[162:165], v0 offset:3072
	s_add_i32 m0, s14, 0xc000
	ds_read_b128 v[166:169], v242
	ds_read_b128 v[170:173], v242 offset:1024
	ds_read_b128 v[174:177], v242 offset:2048
	ds_read_b128 v[178:181], v242 offset:3072
	ds_read_b128 v[204:207], v242 offset:4096
	ds_read_b128 v[208:211], v242 offset:5120
	ds_read_b128 v[212:215], v242 offset:6144
	ds_read_b128 v[216:219], v242 offset:7168
	global_load_lds_dwordx4 v196, s[0:1]
	s_add_i32 m0, s14, 0xe000
	s_nop 0
	global_load_lds_dwordx4 v198, s[0:1]
	s_waitcnt vmcnt(8)
	s_waitcnt lgkmcnt(0)
	s_barrier
	s_setprio 1
	s_waitcnt lgkmcnt(0)
	v_mfma_f32_16x16x32_bf16 v[130:133], v[134:137], v[166:169], v[130:133]
	v_mfma_f32_16x16x32_bf16 v[126:129], v[142:145], v[166:169], v[126:129]
	v_mfma_f32_16x16x32_bf16 v[114:117], v[134:137], v[174:177], v[114:117]
	v_mfma_f32_16x16x32_bf16 v[110:113], v[142:145], v[174:177], v[110:113]
	v_mfma_f32_16x16x32_bf16 v[98:101], v[134:137], v[204:207], v[98:101]
	v_mfma_f32_16x16x32_bf16 v[94:97], v[142:145], v[204:207], v[94:97]
	v_mfma_f32_16x16x32_bf16 v[82:85], v[134:137], v[212:215], v[82:85]
	v_mfma_f32_16x16x32_bf16 v[78:81], v[142:145], v[212:215], v[78:81]
	v_mfma_f32_16x16x32_bf16 v[130:133], v[138:141], v[170:173], v[130:133]
	v_mfma_f32_16x16x32_bf16 v[126:129], v[146:149], v[170:173], v[126:129]
	v_mfma_f32_16x16x32_bf16 v[114:117], v[138:141], v[178:181], v[114:117]
	v_mfma_f32_16x16x32_bf16 v[110:113], v[146:149], v[178:181], v[110:113]
	v_mfma_f32_16x16x32_bf16 v[98:101], v[138:141], v[208:211], v[98:101]
	v_mfma_f32_16x16x32_bf16 v[94:97], v[146:149], v[208:211], v[94:97]
	v_mfma_f32_16x16x32_bf16 v[82:85], v[138:141], v[216:219], v[82:85]
	v_mfma_f32_16x16x32_bf16 v[78:81], v[146:149], v[216:219], v[78:81]
	s_setprio 0
	s_setprio 1
	v_mfma_f32_16x16x32_bf16 v[122:125], v[150:153], v[166:169], v[122:125]
	v_mfma_f32_16x16x32_bf16 v[118:121], v[158:161], v[166:169], v[118:121]
	v_mfma_f32_16x16x32_bf16 v[106:109], v[150:153], v[174:177], v[106:109]
	v_mfma_f32_16x16x32_bf16 v[102:105], v[158:161], v[174:177], v[102:105]
	v_mfma_f32_16x16x32_bf16 v[90:93], v[150:153], v[204:207], v[90:93]
	v_mfma_f32_16x16x32_bf16 v[86:89], v[158:161], v[204:207], v[86:89]
	v_mfma_f32_16x16x32_bf16 v[74:77], v[150:153], v[212:215], v[74:77]
	v_mfma_f32_16x16x32_bf16 v[70:73], v[158:161], v[212:215], v[70:73]
	v_mfma_f32_16x16x32_bf16 v[122:125], v[154:157], v[170:173], v[122:125]
	v_mfma_f32_16x16x32_bf16 v[118:121], v[162:165], v[170:173], v[118:121]
	v_mfma_f32_16x16x32_bf16 v[106:109], v[154:157], v[178:181], v[106:109]
	v_mfma_f32_16x16x32_bf16 v[102:105], v[162:165], v[178:181], v[102:105]
	v_mfma_f32_16x16x32_bf16 v[90:93], v[154:157], v[208:211], v[90:93]
	v_mfma_f32_16x16x32_bf16 v[86:89], v[162:165], v[208:211], v[86:89]
	v_mfma_f32_16x16x32_bf16 v[74:77], v[154:157], v[216:219], v[74:77]
	v_mfma_f32_16x16x32_bf16 v[70:73], v[162:165], v[216:219], v[70:73]
	s_setprio 0
	s_barrier
	s_add_i32 s64, s64, s13
	s_mov_b32 m0, s64
	s_add_u32 s36, s44, 0x80
	s_addc_u32 s37, s45, 0
	ds_read_b128 v[166:169], v242 offset:16384
	ds_read_b128 v[170:173], v242 offset:17408
	ds_read_b128 v[174:177], v242 offset:18432
	ds_read_b128 v[178:181], v242 offset:19456
	ds_read_b128 v[204:207], v242 offset:20480
	ds_read_b128 v[208:211], v242 offset:21504
	ds_read_b128 v[212:215], v242 offset:22528
	ds_read_b128 v[216:219], v242 offset:23552
	global_load_lds_dwordx4 v182, s[44:45]
	s_add_i32 m0, s64, 0x2000
	s_add_i32 s43, s43, s13
	global_load_lds_dwordx4 v186, s[44:45]
	s_add_u32 s44, s44, s8
	s_addc_u32 s45, s45, 0
	s_mov_b32 m0, s43
	s_add_u32 s38, s44, 0x80
	s_addc_u32 s39, s45, 0
	global_load_lds_dwordx4 v182, s[44:45]
	s_add_i32 m0, s43, 0x2000
	s_add_u32 s46, s22, 0x80
	s_addc_u32 s47, s23, 0
	global_load_lds_dwordx4 v186, s[44:45]
	s_mov_b32 m0, s14
	s_nop 0
	global_load_lds_dwordx4 v14, s[22:23]
	s_mov_b32 m0, s15
	s_nop 0
	global_load_lds_dwordx4 v184, s[22:23]
	s_waitcnt vmcnt(8)
	s_waitcnt lgkmcnt(0)
	s_barrier
; #define PG8_STAGE(bufoff, gbase, voff) do { _Pragma("unroll") for (int _i = 0; _i < 2; ++_i) \
;         __builtin_amdgcn_global_load_lds((const unsigned*)((const char*)(gbase) + (voff)[_i]), (LAS unsigned*)(lds + (bufoff) + ldsw + _i * 8192), 16, 0, 0); } while (0)
; #define PG8_LDA(dst, b, h) do { _Pragma("unroll") for (int m = 0; m < 4; ++m) _Pragma("unroll") for (int k = 0; k < 2; ++k) dst[m][k] = *(const LAS bf16x8*)(lds + PG8_SA(b, h) + aoff + m * 2048 + k * 1024); } while (0)
; #define PG8_LDB(dst, b, h) do { _Pragma("unroll") for (int n = 0; n < 2; ++n) _Pragma("unroll") for (int k = 0; k < 2; ++k) dst[n][k] = *(const LAS bf16x8*)(lds + PG8_SB(b, h) + boff + n * 2048 + k * 1024); } while (0)
; #define PG8_MMA(ai, bj, At, Bt) do { __builtin_amdgcn_s_setprio(1); _Pragma("unroll") for (int m = 0; m < 4; ++m) _Pragma("unroll") for (int n = 0; n < 2; ++n) _Pragma("unroll") for (int k = 0; k < 2; ++k) \
;         acc[ai][bj][m][n] = __builtin_amdgcn_mfma_f32_16x16x32_bf16(Bt[n][k], At[m][k], acc[ai][bj][m][n], 0, 0, 0); __builtin_amdgcn_s_setprio(0); } while (0)
; #define PG8_WAIT_V(n) asm volatile("s_waitcnt vmcnt(" #n ")" ::: "memory")
; #define PG8_WAIT_L(n) asm volatile("s_waitcnt lgkmcnt(" #n ")" ::: "memory")
; #define PG8_BAR __builtin_amdgcn_s_barrier()
; #define PG8_SCHED __builtin_amdgcn_sched_barrier(0)
; template <class EpiT>
; __device__ __forceinline__ void gemm_phase(LAS unsigned char* lds, const Gemm g, const StaticOrder& S, const EpiT& E, int wv) {
;     ...
;             PG8_WAIT_V(8); PG8_WAIT_L(0); PG8_BAR; PG8_MMA(1, 0, At, B0); PG8_MMA(1, 1, At, B1); PG8_BAR; PG8_SCHED;
;             PG8_LDB(B0, 1, 0); PG8_LDB(B1, 1, 1); PG8_SCHED; PG8_LDA(At, 1, 0); PG8_STAGE(PG8_SA(0, 1), a2 + hA, voffA);
;             PG8_WAIT_V(8); PG8_WAIT_L(0); PG8_BAR; PG8_MMA(0, 0, At, B0); PG8_MMA(0, 1, At, B1); PG8_BAR; PG8_SCHED;
	s_setprio 1
	s_waitcnt lgkmcnt(0)
	v_mfma_f32_16x16x32_bf16 v[66:69], v[134:137], v[166:169], v[66:69]
	v_mfma_f32_16x16x32_bf16 v[62:65], v[142:145], v[166:169], v[62:65]
	v_mfma_f32_16x16x32_bf16 v[50:53], v[134:137], v[174:177], v[50:53]
	v_mfma_f32_16x16x32_bf16 v[46:49], v[142:145], v[174:177], v[46:49]
	v_mfma_f32_16x16x32_bf16 v[34:37], v[134:137], v[204:207], v[34:37]
	v_mfma_f32_16x16x32_bf16 v[30:33], v[142:145], v[204:207], v[30:33]
	v_mfma_f32_16x16x32_bf16 v[18:21], v[134:137], v[212:215], v[18:21]
	v_mfma_f32_16x16x32_bf16 v[10:13], v[142:145], v[212:215], v[10:13]
	v_mfma_f32_16x16x32_bf16 v[66:69], v[138:141], v[170:173], v[66:69]
	v_mfma_f32_16x16x32_bf16 v[62:65], v[146:149], v[170:173], v[62:65]
	v_mfma_f32_16x16x32_bf16 v[50:53], v[138:141], v[178:181], v[50:53]
	v_mfma_f32_16x16x32_bf16 v[46:49], v[146:149], v[178:181], v[46:49]
	v_mfma_f32_16x16x32_bf16 v[34:37], v[138:141], v[208:211], v[34:37]
	v_mfma_f32_16x16x32_bf16 v[30:33], v[146:149], v[208:211], v[30:33]
	v_mfma_f32_16x16x32_bf16 v[18:21], v[138:141], v[216:219], v[18:21]
	v_mfma_f32_16x16x32_bf16 v[10:13], v[146:149], v[216:219], v[10:13]
	s_setprio 0
	s_setprio 1
	v_mfma_f32_16x16x32_bf16 v[58:61], v[150:153], v[166:169], v[58:61]
	v_mfma_f32_16x16x32_bf16 v[54:57], v[158:161], v[166:169], v[54:57]
	v_mfma_f32_16x16x32_bf16 v[42:45], v[150:153], v[174:177], v[42:45]
	v_mfma_f32_16x16x32_bf16 v[38:41], v[158:161], v[174:177], v[38:41]
	v_mfma_f32_16x16x32_bf16 v[26:29], v[150:153], v[204:207], v[26:29]
	v_mfma_f32_16x16x32_bf16 v[22:25], v[158:161], v[204:207], v[22:25]
	v_mfma_f32_16x16x32_bf16 v[6:9], v[150:153], v[212:215], v[6:9]
	v_mfma_f32_16x16x32_bf16 v[2:5], v[158:161], v[212:215], v[2:5]
	v_mfma_f32_16x16x32_bf16 v[58:61], v[154:157], v[170:173], v[58:61]
	v_mfma_f32_16x16x32_bf16 v[54:57], v[162:165], v[170:173], v[54:57]
	v_mfma_f32_16x16x32_bf16 v[42:45], v[154:157], v[178:181], v[42:45]
	v_mfma_f32_16x16x32_bf16 v[38:41], v[162:165], v[178:181], v[38:41]
	v_mfma_f32_16x16x32_bf16 v[26:29], v[154:157], v[208:211], v[26:29]
	v_mfma_f32_16x16x32_bf16 v[22:25], v[162:165], v[208:211], v[22:25]
	v_mfma_f32_16x16x32_bf16 v[6:9], v[154:157], v[216:219], v[6:9]
	v_mfma_f32_16x16x32_bf16 v[2:5], v[162:165], v[216:219], v[2:5]
	s_setprio 0
	s_barrier
	s_add_i32 s43, 0, 0x18000
	v_add_u32_e32 v0, s43, v234
	s_add_i32 s44, 0, 0x1c000
	ds_read_b128 v[134:137], v0
	ds_read_b128 v[138:141], v0 offset:1024
	ds_read_b128 v[142:145], v0 offset:2048
	ds_read_b128 v[146:149], v0 offset:3072
	v_add_u32_e32 v0, s44, v234
	ds_read_b128 v[150:153], v0
	ds_read_b128 v[154:157], v0 offset:1024
	ds_read_b128 v[158:161], v0 offset:2048
	ds_read_b128 v[162:165], v0 offset:3072
	s_add_u32 s22, s22, s4
	s_addc_u32 s23, s23, 0
	s_mov_b32 m0, s88
	ds_read_b128 v[166:169], v242 offset:32768
	ds_read_b128 v[170:173], v242 offset:33792
	ds_read_b128 v[174:177], v242 offset:34816
	ds_read_b128 v[178:181], v242 offset:35840
	ds_read_b128 v[204:207], v242 offset:36864
	ds_read_b128 v[208:211], v242 offset:37888
	ds_read_b128 v[212:215], v242 offset:38912
	ds_read_b128 v[216:219], v242 offset:39936
	global_load_lds_dwordx4 v14, s[22:23]
	s_mov_b32 m0, s89
	s_nop 0
	global_load_lds_dwordx4 v184, s[22:23]
	s_waitcnt vmcnt(8)
	s_waitcnt lgkmcnt(0)
	s_barrier
	s_setprio 1
	s_waitcnt lgkmcnt(0)
	v_mfma_f32_16x16x32_bf16 v[130:133], v[134:137], v[166:169], v[130:133]
	v_mfma_f32_16x16x32_bf16 v[126:129], v[142:145], v[166:169], v[126:129]
	v_mfma_f32_16x16x32_bf16 v[114:117], v[134:137], v[174:177], v[114:117]
	v_mfma_f32_16x16x32_bf16 v[110:113], v[142:145], v[174:177], v[110:113]
	v_mfma_f32_16x16x32_bf16 v[98:101], v[134:137], v[204:207], v[98:101]
	v_mfma_f32_16x16x32_bf16 v[94:97], v[142:145], v[204:207], v[94:97]
	v_mfma_f32_16x16x32_bf16 v[82:85], v[134:137], v[212:215], v[82:85]
	v_mfma_f32_16x16x32_bf16 v[78:81], v[142:145], v[212:215], v[78:81]
	v_mfma_f32_16x16x32_bf16 v[130:133], v[138:141], v[170:173], v[130:133]
	v_mfma_f32_16x16x32_bf16 v[126:129], v[146:149], v[170:173], v[126:129]
	v_mfma_f32_16x16x32_bf16 v[114:117], v[138:141], v[178:181], v[114:117]
	v_mfma_f32_16x16x32_bf16 v[110:113], v[146:149], v[178:181], v[110:113]
	v_mfma_f32_16x16x32_bf16 v[98:101], v[138:141], v[208:211], v[98:101]
	v_mfma_f32_16x16x32_bf16 v[94:97], v[146:149], v[208:211], v[94:97]
	v_mfma_f32_16x16x32_bf16 v[82:85], v[138:141], v[216:219], v[82:85]
	v_mfma_f32_16x16x32_bf16 v[78:81], v[146:149], v[216:219], v[78:81]
	s_setprio 0
	s_setprio 1
	v_mfma_f32_16x16x32_bf16 v[122:125], v[150:153], v[166:169], v[122:125]
	v_mfma_f32_16x16x32_bf16 v[118:121], v[158:161], v[166:169], v[118:121]
	v_mfma_f32_16x16x32_bf16 v[106:109], v[150:153], v[174:177], v[106:109]
	v_mfma_f32_16x16x32_bf16 v[102:105], v[158:161], v[174:177], v[102:105]
	v_mfma_f32_16x16x32_bf16 v[90:93], v[150:153], v[204:207], v[90:93]
	v_mfma_f32_16x16x32_bf16 v[86:89], v[158:161], v[204:207], v[86:89]
	v_mfma_f32_16x16x32_bf16 v[74:77], v[150:153], v[212:215], v[74:77]
	v_mfma_f32_16x16x32_bf16 v[70:73], v[158:161], v[212:215], v[70:73]
	v_mfma_f32_16x16x32_bf16 v[122:125], v[154:157], v[170:173], v[122:125]
	v_mfma_f32_16x16x32_bf16 v[118:121], v[162:165], v[170:173], v[118:121]
	v_mfma_f32_16x16x32_bf16 v[106:109], v[154:157], v[178:181], v[106:109]
	v_mfma_f32_16x16x32_bf16 v[102:105], v[162:165], v[178:181], v[102:105]
	v_mfma_f32_16x16x32_bf16 v[90:93], v[154:157], v[208:211], v[90:93]
	v_mfma_f32_16x16x32_bf16 v[86:89], v[162:165], v[208:211], v[86:89]
	v_mfma_f32_16x16x32_bf16 v[74:77], v[154:157], v[216:219], v[74:77]
	v_mfma_f32_16x16x32_bf16 v[70:73], v[162:165], v[216:219], v[70:73]
	s_setprio 0
	s_barrier
; #define PG8_STAGE(bufoff, gbase, voff) do { _Pragma("unroll") for (int _i = 0; _i < 2; ++_i) \
;         __builtin_amdgcn_global_load_lds((const unsigned*)((const char*)(gbase) + (voff)[_i]), (LAS unsigned*)(lds + (bufoff) + ldsw + _i * 8192), 16, 0, 0); } while (0)
; #define PG8_LDA(dst, b, h) do { _Pragma("unroll") for (int m = 0; m < 4; ++m) _Pragma("unroll") for (int k = 0; k < 2; ++k) dst[m][k] = *(const LAS bf16x8*)(lds + PG8_SA(b, h) + aoff + m * 2048 + k * 1024); } while (0)
; #define PG8_MMA(ai, bj, At, Bt) do { __builtin_amdgcn_s_setprio(1); _Pragma("unroll") for (int m = 0; m < 4; ++m) _Pragma("unroll") for (int n = 0; n < 2; ++n) _Pragma("unroll") for (int k = 0; k < 2; ++k) \
;         acc[ai][bj][m][n] = __builtin_amdgcn_mfma_f32_16x16x32_bf16(Bt[n][k], At[m][k], acc[ai][bj][m][n], 0, 0, 0); __builtin_amdgcn_s_setprio(0); } while (0)
; #define PG8_WAIT_V(n) asm volatile("s_waitcnt vmcnt(" #n ")" ::: "memory")
; #define PG8_WAIT_L(n) asm volatile("s_waitcnt lgkmcnt(" #n ")" ::: "memory")
; #define PG8_BAR __builtin_amdgcn_s_barrier()
; #define PG8_SCHED __builtin_amdgcn_sched_barrier(0)
; template <class EpiT>
; __device__ __forceinline__ void gemm_phase(LAS unsigned char* lds, const Gemm g, const StaticOrder& S, const EpiT& E, int wv) {
;     ...
;             PG8_LDA(At, 1, 1); PG8_STAGE(PG8_SB(1, 0), b3, voffB); PG8_STAGE(PG8_SB(1, 1), b3 + hB, voffB); PG8_STAGE(PG8_SA(1, 0), a3, voffA);
;             PG8_WAIT_V(8); PG8_WAIT_L(0); PG8_BAR; PG8_MMA(1, 0, At, B0); PG8_MMA(1, 1, At, B1); PG8_BAR; PG8_SCHED;
;         }
	s_add_i32 s22, s43, s13
	s_mov_b32 m0, s22
	ds_read_b128 v[166:169], v242 offset:49152
	ds_read_b128 v[170:173], v242 offset:50176
	ds_read_b128 v[174:177], v242 offset:51200
	ds_read_b128 v[178:181], v242 offset:52224
	ds_read_b128 v[204:207], v242 offset:53248
	ds_read_b128 v[208:211], v242 offset:54272
	ds_read_b128 v[212:215], v242 offset:55296
	ds_read_b128 v[216:219], v242 offset:56320
	global_load_lds_dwordx4 v182, s[36:37]
	s_add_i32 m0, s22, 0x2000
	s_add_i32 s22, s44, s13
	global_load_lds_dwordx4 v186, s[36:37]
	s_mov_b32 m0, s22
	s_nop 0
	global_load_lds_dwordx4 v182, s[38:39]
	s_add_i32 m0, s22, 0x2000
	s_nop 0
	global_load_lds_dwordx4 v186, s[38:39]
	s_mov_b32 m0, s72
	s_nop 0
	global_load_lds_dwordx4 v14, s[46:47]
	s_mov_b32 m0, s73
	s_nop 0
	global_load_lds_dwordx4 v184, s[46:47]
	s_waitcnt vmcnt(8)
	s_waitcnt lgkmcnt(0)
	s_barrier
	s_setprio 1
	s_waitcnt lgkmcnt(0)
	v_mfma_f32_16x16x32_bf16 v[66:69], v[134:137], v[166:169], v[66:69]
	v_mfma_f32_16x16x32_bf16 v[62:65], v[142:145], v[166:169], v[62:65]
	v_mfma_f32_16x16x32_bf16 v[50:53], v[134:137], v[174:177], v[50:53]
	v_mfma_f32_16x16x32_bf16 v[46:49], v[142:145], v[174:177], v[46:49]
	v_mfma_f32_16x16x32_bf16 v[34:37], v[134:137], v[204:207], v[34:37]
	v_mfma_f32_16x16x32_bf16 v[30:33], v[142:145], v[204:207], v[30:33]
	v_mfma_f32_16x16x32_bf16 v[18:21], v[134:137], v[212:215], v[18:21]
	v_mfma_f32_16x16x32_bf16 v[10:13], v[142:145], v[212:215], v[10:13]
	v_mfma_f32_16x16x32_bf16 v[66:69], v[138:141], v[170:173], v[66:69]
	v_mfma_f32_16x16x32_bf16 v[62:65], v[146:149], v[170:173], v[62:65]
	v_mfma_f32_16x16x32_bf16 v[50:53], v[138:141], v[178:181], v[50:53]
	v_mfma_f32_16x16x32_bf16 v[46:49], v[146:149], v[178:181], v[46:49]
	v_mfma_f32_16x16x32_bf16 v[34:37], v[138:141], v[208:211], v[34:37]
	v_mfma_f32_16x16x32_bf16 v[30:33], v[146:149], v[208:211], v[30:33]
	v_mfma_f32_16x16x32_bf16 v[18:21], v[138:141], v[216:219], v[18:21]
	v_mfma_f32_16x16x32_bf16 v[10:13], v[146:149], v[216:219], v[10:13]
	s_setprio 0
	s_setprio 1
	v_mfma_f32_16x16x32_bf16 v[58:61], v[150:153], v[166:169], v[58:61]
	v_mfma_f32_16x16x32_bf16 v[54:57], v[158:161], v[166:169], v[54:57]
	v_mfma_f32_16x16x32_bf16 v[42:45], v[150:153], v[174:177], v[42:45]
	v_mfma_f32_16x16x32_bf16 v[38:41], v[158:161], v[174:177], v[38:41]
	v_mfma_f32_16x16x32_bf16 v[26:29], v[150:153], v[204:207], v[26:29]
	v_mfma_f32_16x16x32_bf16 v[22:25], v[158:161], v[204:207], v[22:25]
	v_mfma_f32_16x16x32_bf16 v[6:9], v[150:153], v[212:215], v[6:9]
	v_mfma_f32_16x16x32_bf16 v[2:5], v[158:161], v[212:215], v[2:5]
	v_mfma_f32_16x16x32_bf16 v[58:61], v[154:157], v[170:173], v[58:61]
	v_mfma_f32_16x16x32_bf16 v[54:57], v[162:165], v[170:173], v[54:57]
	v_mfma_f32_16x16x32_bf16 v[42:45], v[154:157], v[178:181], v[42:45]
	v_mfma_f32_16x16x32_bf16 v[38:41], v[162:165], v[178:181], v[38:41]
	v_mfma_f32_16x16x32_bf16 v[26:29], v[154:157], v[208:211], v[26:29]
	v_mfma_f32_16x16x32_bf16 v[22:25], v[162:165], v[208:211], v[22:25]
	v_mfma_f32_16x16x32_bf16 v[6:9], v[154:157], v[216:219], v[6:9]
	v_mfma_f32_16x16x32_bf16 v[2:5], v[162:165], v[216:219], v[2:5]
	s_setprio 0
	s_barrier
	s_add_u32 s0, s0, 0x100
	s_addc_u32 s1, s1, 0
	s_add_u32 s40, s40, 0x100
	s_addc_u32 s41, s41, 0
	s_cmp_ge_i32 s42, s81
	s_mov_b32 s22, s42
	s_cbranch_scc0 .LBB0_271
	s_and_b64 vcc, exec, s[16:17]
	s_cbranch_vccnz .LBB0_278
